# out-proj (layer 0) fused epilogue: the 4 residual-stream loads of each row group issued together, waits counted (vmcnt(3)) instead of draining loads and stores one by one
# speedup vs baseline: 1.0057x; 1.0042x over previous
; #define PG8_LAS __attribute__((address_space(3)))
;     __device__ __forceinline__ void fused(f32x4 (&acc)[2][2][4][2], const Unit& u, int wr, int wc, int fr, int fq, PG8_LAS unsigned char* lds, int wid, int lane) const {
;         const int row0 = u.pm * BM + wr * 64 + fr; const int col0 = u.pn * BM + wc * 32 + 4 * fq;
;         const int b = (u.pm * BM) >> 11;
;         PG8_LAS float* P = (PG8_LAS float*)lds; PG8_LAS float* S = P + 1024;
;         {
;         f32x4 gt[2][2];
; #pragma unroll
;         for (int bj = 0; bj < 2; ++bj)
; #pragma unroll
;             for (int n = 0; n < 2; ++n) gt[bj][n] = *(const f32x4*)(modf + (size_t)b * 3072 + 2048 + col0 + bj * HALF + 16 * n);
; #pragma unroll
;         for (int ai = 0; ai < 2; ++ai)
; #pragma unroll
;             for (int m = 0; m < 4; ++m) { const size_t ro = (size_t)(row0 + ai * HALF + m * 16) * 1024 + col0; float s = 0.f;
; #pragma unroll
;                 for (int bj = 0; bj < 2; ++bj)
; #pragma unroll
;                     for (int n = 0; n < 2; ++n) { const f32x4 xi = __builtin_nontemporal_load((const f32x4*)(xin + ro + bj * HALF + 16 * n));
;                         const f32x4 v = xi + gt[bj][n] * acc[ai][bj][m][n]; acc[ai][bj][m][n] = v;
;                         *(f32x4*)(xout + ro + bj * HALF + 16 * n) = v;
;                         s += (v[0] * v[0] + v[1] * v[1]) + (v[2] * v[2] + v[3] * v[3]); }
;                 s += __shfl_xor(s, 16); s += __shfl_xor(s, 32);
;                 if (fq == 0) P[(ai * HALF + wr * 64 + m * 16 + fr) * 4 + wc] = s; }
.LBB0_615:
	s_lshl_b32 s30, s20, 8
	s_lshl_b32 s27, s21, 5
	s_add_i32 s36, s30, s5
	s_lshl_b32 s30, s26, 8
	s_or_b32 s27, s30, s27
	v_lshrrev_b32_e32 v132, 2, v191
	v_and_or_b32 v180, v132, 12, s27
	s_ashr_i32 s27, s20, 3
	s_mul_i32 s34, s27, 0x3000
	v_readlane_b32 s30, v253, 48
	s_mul_hi_i32 s33, s27, 0x3000
	v_readlane_b32 s31, v253, 49
	s_add_u32 s30, s30, s34
	s_addc_u32 s31, s31, s33
	v_ashrrev_i32_e32 v181, 31, v180
	v_lshl_add_u64 v[132:133], v[180:181], 2, s[30:31]
	s_movk_i32 s27, 0x2000
	v_add_co_u32_e32 v134, vcc, s27, v132
	v_or_b32_e32 v182, s36, v210
	s_nop 0
	v_addc_co_u32_e32 v135, vcc, 0, v133, vcc
	v_ashrrev_i32_e32 v183, 31, v182
	s_waitcnt vmcnt(0)
	s_barrier
	global_load_dwordx4 v[140:143], v[134:135], off
	v_lshlrev_b64 v[134:135], 10, v[182:183]
	v_lshl_add_u64 v[134:135], v[134:135], 0, v[180:181]
	v_lshlrev_b64 v[154:155], 2, v[134:135]
	v_lshl_add_u64 v[156:157], s[18:19], 0, v[154:155]
	global_load_dwordx4 v[212:215], v[156:157], off nt
	global_load_dwordx4 v[216:219], v[156:157], off offset:64 nt
	global_load_dwordx4 v[220:223], v[156:157], off offset:512 nt
	global_load_dwordx4 v[242:245], v[156:157], off offset:576 nt
	s_mov_b64 s[30:31], 0x2000
	v_lshl_add_u64 v[132:133], v[132:133], 0, s[30:31]
	v_lshl_add_u64 v[158:159], s[78:79], 0, v[154:155]
	global_load_dwordx4 v[144:147], v[132:133], off offset:64
	global_load_dwordx4 v[136:139], v[132:133], off offset:512
	s_nop 0
	global_load_dwordx4 v[132:135], v[132:133], off offset:576
	s_lshl_b32 s21, s21, 2
	v_and_b32_e32 v149, 63, v191
	s_add_i32 s21, s21, 0
	v_lshl_add_u32 v148, v148, 4, s21
	s_waitcnt vmcnt(0)
	v_pk_fma_f32 v[110:111], v[110:111], v[142:143], v[214:215]
	v_pk_fma_f32 v[108:109], v[108:109], v[140:141], v[212:213]
	global_store_dwordx4 v[158:159], v[108:111], off
	v_mul_f32_e32 v160, v111, v111
	v_fmac_f32_e32 v160, v110, v110
	s_waitcnt vmcnt(3)
	v_pk_fma_f32 v[122:123], v[122:123], v[146:147], v[218:219]
	v_pk_fma_f32 v[120:121], v[120:121], v[144:145], v[216:217]
	global_store_dwordx4 v[158:159], v[120:123], off offset:64
	v_mul_f32_e32 v161, v123, v123
	v_fmac_f32_e32 v161, v122, v122
	s_waitcnt vmcnt(3)
	v_pk_fma_f32 v[114:115], v[114:115], v[138:139], v[222:223]
	v_pk_fma_f32 v[112:113], v[112:113], v[136:137], v[220:221]
	global_store_dwordx4 v[158:159], v[112:115], off offset:512
	v_mul_f32_e32 v157, v109, v109
	v_fmac_f32_e32 v157, v108, v108
	v_add_f32_e32 v157, v157, v160
	v_mul_f32_e32 v160, v121, v121
	v_fmac_f32_e32 v160, v120, v120
	v_add_f32_e32 v160, v160, v161
	v_and_b32_e32 v151, 64, v224
	v_add_f32_e32 v157, v157, v160
	v_mul_f32_e32 v160, v113, v113
	v_mul_f32_e32 v161, v115, v115
	v_xor_b32_e32 v150, 16, v224
	v_add_u32_e32 v151, 64, v151
	v_fmac_f32_e32 v160, v112, v112
	v_fmac_f32_e32 v161, v114, v114
	v_cmp_lt_i32_e32 vcc, v150, v151
	v_add_f32_e32 v160, v160, v161
	v_add_f32_e32 v157, v157, v160
	v_cndmask_b32_e32 v150, v224, v150, vcc
	v_lshlrev_b32_e32 v150, 2, v150
	v_xor_b32_e32 v156, 32, v224
	v_cmp_lt_i32_e32 vcc, v156, v151
	s_waitcnt vmcnt(3)
	v_pk_fma_f32 v[130:131], v[130:131], v[134:135], v[244:245]
	v_pk_fma_f32 v[128:129], v[128:129], v[132:133], v[242:243]
	v_mul_f32_e32 v153, v131, v131
	v_mul_f32_e32 v152, v129, v129
	v_fmac_f32_e32 v152, v128, v128
	v_fmac_f32_e32 v153, v130, v130
	v_add_f32_e32 v152, v152, v153
	v_add_f32_e32 v152, v157, v152
	ds_bpermute_b32 v153, v150, v152
	v_cndmask_b32_e32 v151, v224, v156, vcc
	v_lshlrev_b32_e32 v151, 2, v151
	v_cmp_gt_u32_e32 vcc, 16, v149
	global_store_dwordx4 v[158:159], v[128:131], off offset:576
	s_waitcnt lgkmcnt(0)
	v_add_f32_e32 v152, v152, v153
	ds_bpermute_b32 v153, v151, v152
	s_and_saveexec_b64 s[30:31], vcc
	s_cbranch_execz .LBB0_617
	s_waitcnt lgkmcnt(0)
	v_add_f32_e32 v152, v152, v153
	ds_write_b32 v148, v152
.LBB0_617:
	s_or_b64 exec, exec, s[30:31]
	v_or_b32_e32 v184, 16, v182
	v_ashrrev_i32_e32 v185, 31, v184
	s_waitcnt lgkmcnt(0)
	v_lshlrev_b64 v[152:153], 10, v[184:185]
	v_lshl_add_u64 v[152:153], v[152:153], 0, v[180:181]
	v_lshlrev_b64 v[156:157], 2, v[152:153]
	v_lshl_add_u64 v[158:159], s[18:19], 0, v[156:157]
	global_load_dwordx4 v[212:215], v[158:159], off nt
	global_load_dwordx4 v[216:219], v[158:159], off offset:64 nt
	global_load_dwordx4 v[220:223], v[158:159], off offset:512 nt
	global_load_dwordx4 v[242:245], v[158:159], off offset:576 nt
	v_lshl_add_u64 v[156:157], s[78:79], 0, v[156:157]
	s_waitcnt vmcnt(3)
	v_pk_fma_f32 v[126:127], v[126:127], v[142:143], v[214:215]
	v_pk_fma_f32 v[124:125], v[124:125], v[140:141], v[212:213]
	global_store_dwordx4 v[156:157], v[124:127], off
	s_waitcnt vmcnt(3)
	v_pk_fma_f32 v[118:119], v[118:119], v[146:147], v[218:219]
	v_pk_fma_f32 v[116:117], v[116:117], v[144:145], v[216:217]
	global_store_dwordx4 v[156:157], v[116:119], off offset:64
	v_mul_f32_e32 v160, v119, v119
	v_fmac_f32_e32 v160, v118, v118
	s_waitcnt vmcnt(3)
	v_pk_fma_f32 v[106:107], v[106:107], v[138:139], v[222:223]
	v_pk_fma_f32 v[104:105], v[104:105], v[136:137], v[220:221]
	global_store_dwordx4 v[156:157], v[104:107], off offset:512
	v_mul_f32_e32 v158, v125, v125
	v_mul_f32_e32 v159, v127, v127
	v_fmac_f32_e32 v158, v124, v124
	v_fmac_f32_e32 v159, v126, v126
	v_add_f32_e32 v158, v158, v159
	v_mul_f32_e32 v159, v117, v117
	v_fmac_f32_e32 v159, v116, v116
	v_add_f32_e32 v159, v159, v160
	v_add_f32_e32 v158, v158, v159
	v_mul_f32_e32 v159, v105, v105
	v_mul_f32_e32 v160, v107, v107
	v_fmac_f32_e32 v159, v104, v104
	v_fmac_f32_e32 v160, v106, v106
	v_add_f32_e32 v159, v159, v160
	v_add_f32_e32 v158, v158, v159
	s_waitcnt vmcnt(3)
	v_pk_fma_f32 v[102:103], v[102:103], v[134:135], v[244:245]
	v_pk_fma_f32 v[100:101], v[100:101], v[132:133], v[242:243]
	v_mul_f32_e32 v153, v103, v103
	v_mul_f32_e32 v152, v101, v101
	v_fmac_f32_e32 v152, v100, v100
	v_fmac_f32_e32 v153, v102, v102
	v_add_f32_e32 v152, v152, v153
	v_add_f32_e32 v152, v158, v152
	ds_bpermute_b32 v153, v150, v152
	global_store_dwordx4 v[156:157], v[100:103], off offset:576
	s_waitcnt lgkmcnt(0)
	v_add_f32_e32 v152, v152, v153
	ds_bpermute_b32 v153, v151, v152
	s_and_saveexec_b64 s[30:31], vcc
	s_cbranch_execz .LBB0_619
	s_waitcnt lgkmcnt(0)
	v_add_f32_e32 v152, v152, v153
	ds_write_b32 v148, v152 offset:256
;     __device__ __forceinline__ void fused(f32x4 (&acc)[2][2][4][2], const Unit& u, int wr, int wc, int fr, int fq, PG8_LAS unsigned char* lds, int wid, int lane) const {
;     ...
;         for (int ai = 0; ai < 2; ++ai)
; #pragma unroll
;             for (int m = 0; m < 4; ++m) { const size_t ro = (size_t)(row0 + ai * HALF + m * 16) * 1024 + col0; float s = 0.f;
; #pragma unroll
;                 for (int bj = 0; bj < 2; ++bj)
; #pragma unroll
;                     for (int n = 0; n < 2; ++n) { const f32x4 xi = __builtin_nontemporal_load((const f32x4*)(xin + ro + bj * HALF + 16 * n));
;                         const f32x4 v = xi + gt[bj][n] * acc[ai][bj][m][n]; acc[ai][bj][m][n] = v;
;                         *(f32x4*)(xout + ro + bj * HALF + 16 * n) = v;
;                         s += (v[0] * v[0] + v[1] * v[1]) + (v[2] * v[2] + v[3] * v[3]); }
;                 s += __shfl_xor(s, 16); s += __shfl_xor(s, 32);
;                 if (fq == 0) P[(ai * HALF + wr * 64 + m * 16 + fr) * 4 + wc] = s; }
.LBB0_619:
	s_or_b64 exec, exec, s[30:31]
	v_or_b32_e32 v186, 32, v182
	v_ashrrev_i32_e32 v187, 31, v186
	s_waitcnt lgkmcnt(0)
	v_lshlrev_b64 v[152:153], 10, v[186:187]
	v_lshl_add_u64 v[152:153], v[152:153], 0, v[180:181]
	v_lshlrev_b64 v[156:157], 2, v[152:153]
	v_lshl_add_u64 v[158:159], s[18:19], 0, v[156:157]
	global_load_dwordx4 v[212:215], v[158:159], off nt
	global_load_dwordx4 v[216:219], v[158:159], off offset:64 nt
	global_load_dwordx4 v[220:223], v[158:159], off offset:512 nt
	global_load_dwordx4 v[242:245], v[158:159], off offset:576 nt
	v_lshl_add_u64 v[156:157], s[78:79], 0, v[156:157]
	s_waitcnt vmcnt(3)
	v_pk_fma_f32 v[98:99], v[98:99], v[142:143], v[214:215]
	v_pk_fma_f32 v[96:97], v[96:97], v[140:141], v[212:213]
	global_store_dwordx4 v[156:157], v[96:99], off
	s_waitcnt vmcnt(3)
	v_pk_fma_f32 v[94:95], v[94:95], v[146:147], v[218:219]
	v_pk_fma_f32 v[92:93], v[92:93], v[144:145], v[216:217]
	global_store_dwordx4 v[156:157], v[92:95], off offset:64
	v_mul_f32_e32 v160, v95, v95
	v_fmac_f32_e32 v160, v94, v94
	s_waitcnt vmcnt(3)
	v_pk_fma_f32 v[90:91], v[90:91], v[138:139], v[222:223]
	v_pk_fma_f32 v[88:89], v[88:89], v[136:137], v[220:221]
	global_store_dwordx4 v[156:157], v[88:91], off offset:512
	v_mul_f32_e32 v158, v97, v97
	v_mul_f32_e32 v159, v99, v99
	v_fmac_f32_e32 v158, v96, v96
	v_fmac_f32_e32 v159, v98, v98
	v_add_f32_e32 v158, v158, v159
	v_mul_f32_e32 v159, v93, v93
	v_fmac_f32_e32 v159, v92, v92
	v_add_f32_e32 v159, v159, v160
	v_add_f32_e32 v158, v158, v159
	v_mul_f32_e32 v159, v89, v89
	v_mul_f32_e32 v160, v91, v91
	v_fmac_f32_e32 v159, v88, v88
	v_fmac_f32_e32 v160, v90, v90
	v_add_f32_e32 v159, v159, v160
	v_add_f32_e32 v158, v158, v159
	s_waitcnt vmcnt(3)
	v_pk_fma_f32 v[86:87], v[86:87], v[134:135], v[244:245]
	v_pk_fma_f32 v[84:85], v[84:85], v[132:133], v[242:243]
	v_mul_f32_e32 v153, v87, v87
	v_mul_f32_e32 v152, v85, v85
	v_fmac_f32_e32 v152, v84, v84
	v_fmac_f32_e32 v153, v86, v86
	v_add_f32_e32 v152, v152, v153
	v_add_f32_e32 v152, v158, v152
	ds_bpermute_b32 v153, v150, v152
	global_store_dwordx4 v[156:157], v[84:87], off offset:576
	s_waitcnt lgkmcnt(0)
	v_add_f32_e32 v152, v152, v153
	ds_bpermute_b32 v153, v151, v152
	s_and_saveexec_b64 s[30:31], vcc
	s_cbranch_execz .LBB0_621
	s_waitcnt lgkmcnt(0)
	v_add_f32_e32 v152, v152, v153
	ds_write_b32 v148, v152 offset:512
.LBB0_621:
	s_or_b64 exec, exec, s[30:31]
	v_or_b32_e32 v198, 48, v182
	v_ashrrev_i32_e32 v199, 31, v198
	s_waitcnt lgkmcnt(0)
	v_lshlrev_b64 v[152:153], 10, v[198:199]
	v_lshl_add_u64 v[152:153], v[152:153], 0, v[180:181]
	v_lshlrev_b64 v[156:157], 2, v[152:153]
	v_lshl_add_u64 v[158:159], s[18:19], 0, v[156:157]
	global_load_dwordx4 v[212:215], v[158:159], off nt
	global_load_dwordx4 v[216:219], v[158:159], off offset:64 nt
	global_load_dwordx4 v[220:223], v[158:159], off offset:512 nt
	global_load_dwordx4 v[242:245], v[158:159], off offset:576 nt
	v_lshl_add_u64 v[156:157], s[78:79], 0, v[156:157]
	s_waitcnt vmcnt(3)
	v_pk_fma_f32 v[82:83], v[82:83], v[142:143], v[214:215]
	v_pk_fma_f32 v[80:81], v[80:81], v[140:141], v[212:213]
	global_store_dwordx4 v[156:157], v[80:83], off
	s_waitcnt vmcnt(3)
	v_pk_fma_f32 v[78:79], v[78:79], v[146:147], v[218:219]
	v_pk_fma_f32 v[76:77], v[76:77], v[144:145], v[216:217]
	global_store_dwordx4 v[156:157], v[76:79], off offset:64
	v_mul_f32_e32 v160, v79, v79
	v_fmac_f32_e32 v160, v78, v78
	s_waitcnt vmcnt(3)
	v_pk_fma_f32 v[74:75], v[74:75], v[138:139], v[222:223]
	v_pk_fma_f32 v[72:73], v[72:73], v[136:137], v[220:221]
	global_store_dwordx4 v[156:157], v[72:75], off offset:512
	v_mul_f32_e32 v158, v81, v81
	v_mul_f32_e32 v159, v83, v83
	v_fmac_f32_e32 v158, v80, v80
	v_fmac_f32_e32 v159, v82, v82
	v_add_f32_e32 v158, v158, v159
	v_mul_f32_e32 v159, v77, v77
	v_fmac_f32_e32 v159, v76, v76
	v_add_f32_e32 v159, v159, v160
	v_add_f32_e32 v158, v158, v159
	v_mul_f32_e32 v159, v73, v73
	v_mul_f32_e32 v160, v75, v75
	v_fmac_f32_e32 v159, v72, v72
	v_fmac_f32_e32 v160, v74, v74
	v_add_f32_e32 v159, v159, v160
	v_add_f32_e32 v158, v158, v159
	s_waitcnt vmcnt(3)
	v_pk_fma_f32 v[70:71], v[70:71], v[134:135], v[244:245]
	v_pk_fma_f32 v[68:69], v[68:69], v[132:133], v[242:243]
	v_mul_f32_e32 v153, v71, v71
	v_mul_f32_e32 v152, v69, v69
	v_fmac_f32_e32 v152, v68, v68
	v_fmac_f32_e32 v153, v70, v70
	v_add_f32_e32 v152, v152, v153
	v_add_f32_e32 v152, v158, v152
	ds_bpermute_b32 v153, v150, v152
	global_store_dwordx4 v[156:157], v[68:71], off offset:576
	s_waitcnt lgkmcnt(0)
	v_add_f32_e32 v152, v152, v153
	ds_bpermute_b32 v153, v151, v152
	s_and_saveexec_b64 s[30:31], vcc
	s_cbranch_execz .LBB0_623
	s_waitcnt lgkmcnt(0)
	v_add_f32_e32 v152, v152, v153
	ds_write_b32 v148, v152 offset:768
;     __device__ __forceinline__ void fused(f32x4 (&acc)[2][2][4][2], const Unit& u, int wr, int wc, int fr, int fq, PG8_LAS unsigned char* lds, int wid, int lane) const {
;     ...
;         for (int ai = 0; ai < 2; ++ai)
; #pragma unroll
;             for (int m = 0; m < 4; ++m) { const size_t ro = (size_t)(row0 + ai * HALF + m * 16) * 1024 + col0; float s = 0.f;
; #pragma unroll
;                 for (int bj = 0; bj < 2; ++bj)
; #pragma unroll
;                     for (int n = 0; n < 2; ++n) { const f32x4 xi = __builtin_nontemporal_load((const f32x4*)(xin + ro + bj * HALF + 16 * n));
;                         const f32x4 v = xi + gt[bj][n] * acc[ai][bj][m][n]; acc[ai][bj][m][n] = v;
;                         *(f32x4*)(xout + ro + bj * HALF + 16 * n) = v;
;                         s += (v[0] * v[0] + v[1] * v[1]) + (v[2] * v[2] + v[3] * v[3]); }
;                 s += __shfl_xor(s, 16); s += __shfl_xor(s, 32);
;                 if (fq == 0) P[(ai * HALF + wr * 64 + m * 16 + fr) * 4 + wc] = s; }
.LBB0_623:
	s_or_b64 exec, exec, s[30:31]
	v_add_u32_e32 v200, 0x80, v182
	v_ashrrev_i32_e32 v201, 31, v200
	s_waitcnt lgkmcnt(0)
	v_lshlrev_b64 v[152:153], 10, v[200:201]
	v_lshl_add_u64 v[152:153], v[152:153], 0, v[180:181]
	v_lshlrev_b64 v[156:157], 2, v[152:153]
	v_lshl_add_u64 v[158:159], s[18:19], 0, v[156:157]
	global_load_dwordx4 v[212:215], v[158:159], off nt
	global_load_dwordx4 v[216:219], v[158:159], off offset:64 nt
	global_load_dwordx4 v[220:223], v[158:159], off offset:512 nt
	global_load_dwordx4 v[242:245], v[158:159], off offset:576 nt
	v_lshl_add_u64 v[156:157], s[78:79], 0, v[156:157]
	s_waitcnt vmcnt(3)
	v_pk_fma_f32 v[66:67], v[66:67], v[142:143], v[214:215]
	v_pk_fma_f32 v[64:65], v[64:65], v[140:141], v[212:213]
	global_store_dwordx4 v[156:157], v[64:67], off
	s_waitcnt vmcnt(3)
	v_pk_fma_f32 v[62:63], v[62:63], v[146:147], v[218:219]
	v_pk_fma_f32 v[60:61], v[60:61], v[144:145], v[216:217]
	global_store_dwordx4 v[156:157], v[60:63], off offset:64
	v_mul_f32_e32 v160, v63, v63
	v_fmac_f32_e32 v160, v62, v62
	s_waitcnt vmcnt(3)
	v_pk_fma_f32 v[58:59], v[58:59], v[138:139], v[222:223]
	v_pk_fma_f32 v[56:57], v[56:57], v[136:137], v[220:221]
	global_store_dwordx4 v[156:157], v[56:59], off offset:512
	v_mul_f32_e32 v158, v65, v65
	v_mul_f32_e32 v159, v67, v67
	v_fmac_f32_e32 v158, v64, v64
	v_fmac_f32_e32 v159, v66, v66
	v_add_f32_e32 v158, v158, v159
	v_mul_f32_e32 v159, v61, v61
	v_fmac_f32_e32 v159, v60, v60
	v_add_f32_e32 v159, v159, v160
	v_add_f32_e32 v158, v158, v159
	v_mul_f32_e32 v159, v57, v57
	v_mul_f32_e32 v160, v59, v59
	v_fmac_f32_e32 v159, v56, v56
	v_fmac_f32_e32 v160, v58, v58
	v_add_f32_e32 v159, v159, v160
	v_add_f32_e32 v158, v158, v159
	s_waitcnt vmcnt(3)
	v_pk_fma_f32 v[54:55], v[54:55], v[134:135], v[244:245]
	v_pk_fma_f32 v[52:53], v[52:53], v[132:133], v[242:243]
	v_mul_f32_e32 v153, v55, v55
	v_mul_f32_e32 v152, v53, v53
	v_fmac_f32_e32 v152, v52, v52
	v_fmac_f32_e32 v153, v54, v54
	v_add_f32_e32 v152, v152, v153
	v_add_f32_e32 v152, v158, v152
	ds_bpermute_b32 v153, v150, v152
	global_store_dwordx4 v[156:157], v[52:55], off offset:576
	s_waitcnt lgkmcnt(0)
	v_add_f32_e32 v152, v152, v153
	ds_bpermute_b32 v153, v151, v152
	s_and_saveexec_b64 s[30:31], vcc
	s_cbranch_execz .LBB0_625
	s_waitcnt lgkmcnt(0)
	v_add_f32_e32 v152, v152, v153
	ds_write_b32 v148, v152 offset:2048
.LBB0_625:
	s_or_b64 exec, exec, s[30:31]
	v_add_u32_e32 v202, 0x90, v182
	v_ashrrev_i32_e32 v203, 31, v202
	s_waitcnt lgkmcnt(0)
	v_lshlrev_b64 v[152:153], 10, v[202:203]
	v_lshl_add_u64 v[152:153], v[152:153], 0, v[180:181]
	v_lshlrev_b64 v[156:157], 2, v[152:153]
	v_lshl_add_u64 v[158:159], s[18:19], 0, v[156:157]
	global_load_dwordx4 v[212:215], v[158:159], off nt
	global_load_dwordx4 v[216:219], v[158:159], off offset:64 nt
	global_load_dwordx4 v[220:223], v[158:159], off offset:512 nt
	global_load_dwordx4 v[242:245], v[158:159], off offset:576 nt
	v_lshl_add_u64 v[156:157], s[78:79], 0, v[156:157]
	s_waitcnt vmcnt(3)
	v_pk_fma_f32 v[50:51], v[50:51], v[142:143], v[214:215]
	v_pk_fma_f32 v[48:49], v[48:49], v[140:141], v[212:213]
	global_store_dwordx4 v[156:157], v[48:51], off
	s_waitcnt vmcnt(3)
	v_pk_fma_f32 v[46:47], v[46:47], v[146:147], v[218:219]
	v_pk_fma_f32 v[44:45], v[44:45], v[144:145], v[216:217]
	global_store_dwordx4 v[156:157], v[44:47], off offset:64
	v_mul_f32_e32 v160, v47, v47
	v_fmac_f32_e32 v160, v46, v46
	s_waitcnt vmcnt(3)
	v_pk_fma_f32 v[42:43], v[42:43], v[138:139], v[222:223]
	v_pk_fma_f32 v[40:41], v[40:41], v[136:137], v[220:221]
	global_store_dwordx4 v[156:157], v[40:43], off offset:512
	v_mul_f32_e32 v158, v49, v49
	v_mul_f32_e32 v159, v51, v51
	v_fmac_f32_e32 v158, v48, v48
	v_fmac_f32_e32 v159, v50, v50
	v_add_f32_e32 v158, v158, v159
	v_mul_f32_e32 v159, v45, v45
	v_fmac_f32_e32 v159, v44, v44
	v_add_f32_e32 v159, v159, v160
	v_add_f32_e32 v158, v158, v159
	v_mul_f32_e32 v159, v41, v41
	v_mul_f32_e32 v160, v43, v43
	v_fmac_f32_e32 v159, v40, v40
	v_fmac_f32_e32 v160, v42, v42
	v_add_f32_e32 v159, v159, v160
	v_add_f32_e32 v158, v158, v159
	s_waitcnt vmcnt(3)
	v_pk_fma_f32 v[38:39], v[38:39], v[134:135], v[244:245]
	v_pk_fma_f32 v[36:37], v[36:37], v[132:133], v[242:243]
	v_mul_f32_e32 v153, v39, v39
	v_mul_f32_e32 v152, v37, v37
	v_fmac_f32_e32 v152, v36, v36
	v_fmac_f32_e32 v153, v38, v38
	v_add_f32_e32 v152, v152, v153
	v_add_f32_e32 v152, v158, v152
	ds_bpermute_b32 v153, v150, v152
	global_store_dwordx4 v[156:157], v[36:39], off offset:576
	s_waitcnt lgkmcnt(0)
	v_add_f32_e32 v152, v152, v153
	ds_bpermute_b32 v153, v151, v152
	s_and_saveexec_b64 s[30:31], vcc
	s_cbranch_execz .LBB0_627
	s_waitcnt lgkmcnt(0)
	v_add_f32_e32 v152, v152, v153
	ds_write_b32 v148, v152 offset:2304
;     __device__ __forceinline__ void fused(f32x4 (&acc)[2][2][4][2], const Unit& u, int wr, int wc, int fr, int fq, PG8_LAS unsigned char* lds, int wid, int lane) const {
;     ...
;         for (int ai = 0; ai < 2; ++ai)
; #pragma unroll
;             for (int m = 0; m < 4; ++m) { const size_t ro = (size_t)(row0 + ai * HALF + m * 16) * 1024 + col0; float s = 0.f;
; #pragma unroll
;                 for (int bj = 0; bj < 2; ++bj)
; #pragma unroll
;                     for (int n = 0; n < 2; ++n) { const f32x4 xi = __builtin_nontemporal_load((const f32x4*)(xin + ro + bj * HALF + 16 * n));
;                         const f32x4 v = xi + gt[bj][n] * acc[ai][bj][m][n]; acc[ai][bj][m][n] = v;
;                         *(f32x4*)(xout + ro + bj * HALF + 16 * n) = v;
;                         s += (v[0] * v[0] + v[1] * v[1]) + (v[2] * v[2] + v[3] * v[3]); }
;                 s += __shfl_xor(s, 16); s += __shfl_xor(s, 32);
;                 if (fq == 0) P[(ai * HALF + wr * 64 + m * 16 + fr) * 4 + wc] = s; }
.LBB0_627:
	s_or_b64 exec, exec, s[30:31]
	v_add_u32_e32 v204, 0xa0, v182
	v_ashrrev_i32_e32 v205, 31, v204
	s_waitcnt lgkmcnt(0)
	v_lshlrev_b64 v[152:153], 10, v[204:205]
	v_lshl_add_u64 v[152:153], v[152:153], 0, v[180:181]
	v_lshlrev_b64 v[156:157], 2, v[152:153]
	v_lshl_add_u64 v[158:159], s[18:19], 0, v[156:157]
	global_load_dwordx4 v[212:215], v[158:159], off nt
	global_load_dwordx4 v[216:219], v[158:159], off offset:64 nt
	global_load_dwordx4 v[220:223], v[158:159], off offset:512 nt
	global_load_dwordx4 v[242:245], v[158:159], off offset:576 nt
	v_lshl_add_u64 v[156:157], s[78:79], 0, v[156:157]
	s_waitcnt vmcnt(3)
	v_pk_fma_f32 v[34:35], v[34:35], v[142:143], v[214:215]
	v_pk_fma_f32 v[32:33], v[32:33], v[140:141], v[212:213]
	global_store_dwordx4 v[156:157], v[32:35], off
	s_waitcnt vmcnt(3)
	v_pk_fma_f32 v[30:31], v[30:31], v[146:147], v[218:219]
	v_pk_fma_f32 v[28:29], v[28:29], v[144:145], v[216:217]
	global_store_dwordx4 v[156:157], v[28:31], off offset:64
	v_mul_f32_e32 v160, v31, v31
	v_fmac_f32_e32 v160, v30, v30
	s_waitcnt vmcnt(3)
	v_pk_fma_f32 v[26:27], v[26:27], v[138:139], v[222:223]
	v_pk_fma_f32 v[24:25], v[24:25], v[136:137], v[220:221]
	global_store_dwordx4 v[156:157], v[24:27], off offset:512
	v_mul_f32_e32 v158, v33, v33
	v_mul_f32_e32 v159, v35, v35
	v_fmac_f32_e32 v158, v32, v32
	v_fmac_f32_e32 v159, v34, v34
	v_add_f32_e32 v158, v158, v159
	v_mul_f32_e32 v159, v29, v29
	v_fmac_f32_e32 v159, v28, v28
	v_add_f32_e32 v159, v159, v160
	v_add_f32_e32 v158, v158, v159
	v_mul_f32_e32 v159, v25, v25
	v_mul_f32_e32 v160, v27, v27
	v_fmac_f32_e32 v159, v24, v24
	v_fmac_f32_e32 v160, v26, v26
	v_add_f32_e32 v159, v159, v160
	v_add_f32_e32 v158, v158, v159
	s_waitcnt vmcnt(3)
	v_pk_fma_f32 v[22:23], v[22:23], v[134:135], v[244:245]
	v_pk_fma_f32 v[20:21], v[20:21], v[132:133], v[242:243]
	v_mul_f32_e32 v153, v23, v23
	v_mul_f32_e32 v152, v21, v21
	v_fmac_f32_e32 v152, v20, v20
	v_fmac_f32_e32 v153, v22, v22
	v_add_f32_e32 v152, v152, v153
	v_add_f32_e32 v152, v158, v152
	ds_bpermute_b32 v153, v150, v152
	global_store_dwordx4 v[156:157], v[20:23], off offset:576
	s_waitcnt lgkmcnt(0)
	v_add_f32_e32 v152, v152, v153
	ds_bpermute_b32 v153, v151, v152
	s_and_saveexec_b64 s[30:31], vcc
	s_cbranch_execz .LBB0_629
	s_waitcnt lgkmcnt(0)
	v_add_f32_e32 v152, v152, v153
	ds_write_b32 v148, v152 offset:2560
.LBB0_629:
	s_or_b64 exec, exec, s[30:31]
	v_add_u32_e32 v206, 0xb0, v182
	v_ashrrev_i32_e32 v207, 31, v206
	s_waitcnt lgkmcnt(0)
	v_lshlrev_b64 v[152:153], 10, v[206:207]
	v_lshl_add_u64 v[152:153], v[152:153], 0, v[180:181]
	v_lshlrev_b64 v[156:157], 2, v[152:153]
	v_lshl_add_u64 v[158:159], s[18:19], 0, v[156:157]
	global_load_dwordx4 v[212:215], v[158:159], off nt
	global_load_dwordx4 v[216:219], v[158:159], off offset:64 nt
	global_load_dwordx4 v[220:223], v[158:159], off offset:512 nt
	global_load_dwordx4 v[242:245], v[158:159], off offset:576 nt
	v_lshl_add_u64 v[156:157], s[78:79], 0, v[156:157]
	s_waitcnt vmcnt(3)
	v_pk_fma_f32 v[18:19], v[18:19], v[142:143], v[214:215]
	v_pk_fma_f32 v[16:17], v[16:17], v[140:141], v[212:213]
	global_store_dwordx4 v[156:157], v[16:19], off
	s_waitcnt vmcnt(3)
	v_pk_fma_f32 v[14:15], v[14:15], v[146:147], v[218:219]
	v_pk_fma_f32 v[12:13], v[12:13], v[144:145], v[216:217]
	global_store_dwordx4 v[156:157], v[12:15], off offset:64
	s_waitcnt vmcnt(3)
	v_pk_fma_f32 v[10:11], v[10:11], v[138:139], v[222:223]
	v_pk_fma_f32 v[8:9], v[8:9], v[136:137], v[220:221]
	global_store_dwordx4 v[156:157], v[8:11], off offset:512
	v_mul_f32_e32 v140, v17, v17
	v_mul_f32_e32 v141, v19, v19
	v_fmac_f32_e32 v140, v16, v16
	v_fmac_f32_e32 v141, v18, v18
	v_add_f32_e32 v140, v140, v141
	v_mul_f32_e32 v141, v13, v13
	v_mul_f32_e32 v142, v15, v15
	v_fmac_f32_e32 v141, v12, v12
	v_fmac_f32_e32 v142, v14, v14
	v_add_f32_e32 v141, v141, v142
	v_add_f32_e32 v140, v140, v141
	v_mul_f32_e32 v141, v9, v9
	v_mul_f32_e32 v142, v11, v11
	v_fmac_f32_e32 v141, v8, v8
	v_fmac_f32_e32 v142, v10, v10
	v_add_f32_e32 v141, v141, v142
	v_add_f32_e32 v140, v140, v141
	s_waitcnt vmcnt(3)
	v_pk_fma_f32 v[6:7], v[6:7], v[134:135], v[244:245]
	v_pk_fma_f32 v[4:5], v[4:5], v[132:133], v[242:243]
	v_mul_f32_e32 v133, v7, v7
	v_mul_f32_e32 v132, v5, v5
	v_fmac_f32_e32 v132, v4, v4
	v_fmac_f32_e32 v133, v6, v6
	v_add_f32_e32 v132, v132, v133
	v_add_f32_e32 v132, v140, v132
	ds_bpermute_b32 v133, v150, v132
	global_store_dwordx4 v[156:157], v[4:7], off offset:576
	s_waitcnt lgkmcnt(0)
	v_add_f32_e32 v132, v132, v133
	ds_bpermute_b32 v133, v151, v132
	s_and_saveexec_b64 s[30:31], vcc
	s_cbranch_execz .LBB0_631
	s_waitcnt lgkmcnt(0)
	v_add_f32_e32 v132, v132, v133
	ds_write_b32 v148, v132 offset:2816
